# hideconv2
# speedup vs baseline: 1.0013x; 1.0013x over previous
; DI void conv_layer(const Ctx& c, const Args& a, int L, LAS unsigned char* lds, int gw, int NGW, int wave, int lane) {
;     LAS float* scr = (LAS float*)(lds + wave * 8704);
;     const float* Win = a.in[2] + (size_t)L * DM * 9752;
;     const float* Wg = a.in[15] + (size_t)L * DM * DFF; const float* Wu = a.in[16] + (size_t)L * DM * DFF; const float* Wd = a.in[17] + (size_t)L * DFF * DM;
;     ...
;     constexpr int NITEMS = (9984 / 32) * 32 + 3 * 64 * 8 + 64 * 32 + 2 * 176 * 32 + 64 * 88 + 2 * 8 * 32 + 2 * 2 * 4;
;     for (int it = gw; it < NITEMS; it += NGW) {
;         int rr = it;
;         SEG(Win, 9752, 2048, 3608, c.WinT, 3840, 192, 6144)
;         SEG(Win, 9752, 2048, 0, c.WinT, 0, 16, 512)
;         SEG(Win, 9752, 2048, 512, c.WinT, 2048, 4, 128)
;         SEG(Win, 9752, 2048, 640, c.WinT, 2816, 4, 128)
;         SEG(Win, 9752, 2048, 768, c.WinT, 512, 16, 512)
;         SEG(Win, 9752, 2048, 1280, c.WinT, 1024, 16, 512)
;         SEG(Win, 9752, 2048, 1792, c.WinT, 3328, 16, 512)
;         SEG(Win, 9752, 2048, 2304, c.WinT, 1536, 16, 512)
;         SEG(Win, 9752, 2048, 2816, c.WinT, 2176, 4, 128)
;         SEG(Win, 9752, 2048, 2944, c.WinT, 2304, 4, 128)
;         SEG(Win, 9752, 2048, 3072, c.WinT, 2432, 4, 128)
;         SEG(Win, 9752, 2048, 3200, c.WinT, 2944, 4, 128)
;         SEG(Win, 9752, 2048, 3328, c.WinT, 2560, 4, 128)
;         SEG(Win, 9752, 2048, 3456, c.WinT, 3072, 4, 128)
;         SEG(Win, 9752, 2048, 3584, c.WinT, 2688, 4, 24)
;         SEG(Win, 9752, 2048, 0, c.WinT, 3200, 4, 0)
;         SEG(a.in[10] + (size_t)L * 512 * DM, 2048, 512, 0, c.WbrT, 0, 64, 2048)
;         SEG(a.in[11] + (size_t)L * 512 * DM, 2048, 512, 0, c.WbrT + (size_t)2048 * 512, 0, 64, 2048)
;         SEG(a.in[12] + (size_t)L * 512 * DM, 2048, 512, 0, c.WbrT + (size_t)2 * 2048 * 512, 0, 64, 2048)
;         SEG(a.in[13] + (size_t)L * DM * DM, 2048, 2048, 0, c.WoutT, 0, 64, 2048)
;         { const int cnt = 176 * 32; if (rr < cnt) { const int kb = rr / 176, j = rr % 176; transpose_item(Wg, DFF, 2048, 64 * kb, 32 * j, 32, c.WguT, (j >> 2) * 256 + (j & 3) * 32, scr, lane); continue; } rr -= cnt; }
;         { const int cnt = 176 * 32; if (rr < cnt) { const int kb = rr / 176, j = rr % 176; transpose_item(Wu, DFF, 2048, 64 * kb, 32 * j, 32, c.WguT, (j >> 2) * 256 + 128 + (j & 3) * 32, scr, lane); continue; } rr -= cnt; }
;         SEG(Wd, 2048, 5632, 0, c.WdT, 0, 64, 2048)
.Lcq_entry:
	v_readlane_b32 s54, v244, 1
	v_readlane_b32 s55, v244, 2
	s_load_dwordx4 s[24:27], s[54:55], 0x0
	s_load_dwordx2 s[6:7], s[54:55], 0x10
	s_load_dwordx16 s[36:51], s[54:55], 0x20
	s_load_dwordx4 s[12:15], s[54:55], 0x98
	v_readlane_b32 s17, v244, 7
	v_readlane_b32 s34, v244, 0
	v_mbcnt_lo_u32_b32 v34, -1, 0
	v_mbcnt_hi_u32_b32 v34, -1, v34
	s_lshl_b32 s8, s34, 3
	s_mov_b32 s52, s84
	s_add_i32 s16, s8, s17
	s_ashr_i32 s53, s52, 31
	s_mov_b32 s31, s84
	s_cmpk_gt_i32 s16, 0x790f
	s_cbranch_scc1 .LBB0_1426
	s_load_dwordx4 s[8:11], s[54:55], 0x60
	s_load_dwordx4 s[84:87], s[54:55], 0x78
	s_nop 0
	s_load_dwordx2 s[54:55], s[54:55], 0x88
	s_mul_i32 s63, s52, 0x4c30000
	s_mul_hi_i32 s62, s52, 0x4c30000
	s_waitcnt lgkmcnt(0)
	s_add_u32 s6, s6, s63
	s_addc_u32 s7, s7, s62
	s_mul_i32 s62, s17, 0x2200
	s_add_i32 s72, s62, 0x10000
	s_cmp_eq_u32 s72, 0x1ee00
	s_cselect_b32 s72, 0x20100, s72
	s_mul_i32 s66, s52, 0x2c00000
	s_mul_hi_i32 s67, s52, 0x2c00000
	s_add_u32 s54, s54, s66
	s_addc_u32 s55, s55, s67
	s_waitcnt vmcnt(0)
	v_and_b32_e32 v2, 7, v34
	s_add_u32 s62, s86, s66
	v_ashrrev_i32_e32 v35, 3, v34
	v_lshlrev_b32_e32 v0, 4, v2
	s_movk_i32 s73, 0x84
	s_addc_u32 s63, s87, s67
	v_add_u32_e32 v37, s72, v0
	v_mul_lo_u32 v3, v35, s73
	s_add_u32 s66, s84, s66
	v_lshlrev_b32_e32 v36, 2, v2
	v_add_u32_e32 v86, v37, v3
	v_add_u32_e32 v88, 0x420, v3
	v_mul_u32_u24_e32 v2, 0x420, v2
	v_lshlrev_b32_e32 v3, 2, v35
	s_addc_u32 s67, s85, s67
	v_add3_u32 v91, s72, v2, v3
	s_lshl_b64 s[72:73], s[52:53], 22
	s_lshl_b64 s[84:85], s[52:53], 24
	v_lshl_add_u64 v[42:43], s[62:63], 0, v[0:1]
	v_lshl_add_u64 v[44:45], s[54:55], 0, v[0:1]
	s_lshl_b64 s[54:55], s[52:53], 21
	s_lshl_b64 s[62:63], s[52:53], 16
	s_add_u32 s48, s48, s72
	s_addc_u32 s49, s49, s73
	v_lshl_add_u64 v[68:69], s[48:49], 0, v[0:1]
	s_add_u32 s48, s50, s72
	s_addc_u32 s49, s51, s73
	s_add_u32 s8, s8, s72
	s_addc_u32 s9, s9, s73
	v_lshl_add_u64 v[40:41], s[66:67], 0, v[0:1]
	v_lshl_add_u64 v[46:47], s[14:15], 0, v[0:1]
	s_mov_b64 s[66:67], 0x2700000
	v_lshl_add_u64 v[72:73], s[8:9], 0, v[0:1]
	s_add_u32 s8, s10, s84
	v_lshl_add_u64 v[48:49], v[46:47], 0, s[66:67]
	s_mov_b64 s[66:67], 0x2d00000
	s_addc_u32 s9, s11, s85
	v_lshl_add_u64 v[50:51], v[46:47], 0, s[66:67]
	s_mov_b64 s[66:67], 0x3500000
	v_lshl_add_u64 v[74:75], s[8:9], 0, v[0:1]
	s_add_u32 s8, s38, s54
	v_lshl_add_u64 v[52:53], v[46:47], 0, s[66:67]
	s_mov_b64 s[66:67], 0x6100000
	s_addc_u32 s9, s39, s55
	v_lshl_add_u64 v[54:55], v[46:47], 0, s[66:67]
	s_mov_b64 s[66:67], 0x7700000
	v_lshl_add_u64 v[76:77], s[8:9], 0, v[0:1]
	s_add_u32 s8, s44, s54
	v_lshl_add_u64 v[56:57], v[46:47], 0, s[66:67]
	s_mov_b64 s[66:67], 0x7800000
	s_addc_u32 s9, s45, s55
	v_lshl_add_u64 v[58:59], v[46:47], 0, s[66:67]
	s_mov_b64 s[66:67], 0x7900000
	v_lshl_add_u64 v[78:79], s[8:9], 0, v[0:1]
	s_add_u32 s8, s40, s62
	v_lshl_add_u64 v[60:61], v[46:47], 0, s[66:67]
	s_mov_b64 s[66:67], 0x7908000
	s_addc_u32 s9, s41, s63
	v_lshl_add_u64 v[62:63], v[46:47], 0, s[66:67]
	s_mov_b64 s[66:67], 0x2900000
	v_lshl_add_u64 v[80:81], s[8:9], 0, v[0:1]
	s_add_u32 s8, s46, s62
	v_lshl_add_u64 v[64:65], v[46:47], 0, s[66:67]
	s_mov_b64 s[66:67], 0x2b00000
	s_addc_u32 s9, s47, s63
	v_add_u32_e32 v87, 8, v35
	v_add_u32_e32 v89, 16, v35
	v_add_u32_e32 v90, 24, v35
	v_lshl_add_u64 v[38:39], s[6:7], 0, v[0:1]
	v_lshl_add_u64 v[66:67], v[46:47], 0, s[66:67]
	v_lshl_add_u64 v[70:71], s[48:49], 0, v[0:1]
	v_lshl_add_u64 v[82:83], s[8:9], 0, v[0:1]
	s_cmp_eq_u32 s100, 0
	s_cbranch_scc0 .Lcq_job
	s_cmp_lg_u32 s52, 0
	s_cbranch_scc1 .Lcq_rms_fix
	s_mov_b32 s100, 5
	s_branch .Lcq_pb
.Lcq_job:
	s_cmpk_ge_u32 s100, 5
	s_cbranch_scc1 .Lcq_pb
	s_branch .Lcq_pop
.LBB0_1262:
	s_add_i32 s101, s101, 8
	s_bfe_u32 vcc_lo, s101, 0x20003
	s_cmp_lg_u32 vcc_lo, 0
	s_cbranch_scc1 .Lcq_map
.Lcq_pop:
	s_and_b32 s101, s34, 7
	s_lshl_b32 s101, s101, 8
	s_lshl_b32 vcc_lo, s100, 11
	s_add_i32 s101, s101, vcc_lo
	s_add_i32 s101, s101, 0x2220c000
	v_mov_b32_e32 v245, 1
	v_mov_b32_e32 v247, s101
	s_mov_b64 vcc, exec
	s_mov_b64 exec, 1
	global_atomic_add v246, v247, v245, s[14:15] sc0
	s_mov_b64 exec, vcc
	s_waitcnt vmcnt(0)
	v_readfirstlane_b32 s101, v246
	s_and_b32 vcc_lo, s34, 7
	s_lshl_b32 s101, s101, 5
	s_add_i32 s101, s101, vcc_lo

; __global__ void __launch_bounds__(512) fwd(Args a_) {
;     ...
;         } else if (PHM(0) && sp == 0) { PHASE_PROLOGUE
;             conv_layer(c, a, L, lds, gw, NGW, wave, lane);
;             for (int it = gw; it < 128; it += NGW) {
;                 const int kv = it >> 6, ch = (it >> 2) & 15, hid = (it & 3) * 64 + lane;
;                 const float* w1 = (kv ? a.in[8] : a.in[5]) + (size_t)L * 2048 * 256 + (size_t)(ch * 128) * 256 + hid;
;                 const float* pe = (kv ? a.in[7] : a.in[4]) + (size_t)L * 2048 + ch * 128;
;                 float s = 0.f;
; #pragma unroll 16
;                 for (int k = 0; k < 128; ++k) s += pe[k] * w1[(size_t)k * 256];
;                 ((float*)(a.ws + WS_PB))[kv * 4096 + ch * 256 + hid] = s;
.LBB0_1426:
	s_cmp_eq_u32 s100, 4
	s_cbranch_scc1 .Lcq_to_rms
	s_branch .Lcq_return
.Lcq_pb:
	s_cmpk_gt_i32 s16, 0x7f
	v_ashrrev_i32_e32 v35, 31, v34
	s_cbranch_scc1 .LBB0_1431
	s_waitcnt lgkmcnt(0)
	s_lshl_b64 s[6:7], s[52:53], 21
	s_lshl_b64 s[10:11], s[52:53], 13
	s_add_u32 s40, s14, 0x22210000
	s_addc_u32 s41, s15, 0
	s_waitcnt vmcnt(0)
	v_lshl_add_u64 v[2:3], v[34:35], 2, s[6:7]
	s_lshl_b32 s6, s34, 9
	s_lshl_b32 s7, s17, 6
	s_add_i32 s17, s6, s7
	s_mov_b32 s50, s16

; __global__ void __launch_bounds__(512) fwd(Args a_) {
;     ...
;         } else if (PHM(0) && sp == 0) { PHASE_PROLOGUE
;             conv_layer(c, a, L, lds, gw, NGW, wave, lane);
;             for (int it = gw; it < 128; it += NGW) {
;                 const int kv = it >> 6, ch = (it >> 2) & 15, hid = (it & 3) * 64 + lane;
;                 const float* w1 = (kv ? a.in[8] : a.in[5]) + (size_t)L * 2048 * 256 + (size_t)(ch * 128) * 256 + hid;
;                 const float* pe = (kv ? a.in[7] : a.in[4]) + (size_t)L * 2048 + ch * 128;
;                 float s = 0.f;
; #pragma unroll 16
;                 for (int k = 0; k < 128; ++k) s += pe[k] * w1[(size_t)k * 256];
;                 ((float*)(a.ws + WS_PB))[kv * 4096 + ch * 256 + hid] = s;
;             }
;             const float* xs = L == 0 ? a.in[0] : X;
;             for (int row = gw; row < SEQ; row += NGW) rms_row_bf16(xs + (size_t)row * DM, a.in[1] + L * DM, c.H + (size_t)row * DM, lane);
.LBB0_1431:
	s_cmp_eq_u32 s100, 5
	s_cbranch_scc1 .Lcq_pb5done
	s_cmp_eq_u32 s100, 6
	s_cbranch_scc1 .Lcq_pb6done
	s_branch .Lcq_rms
.Lcq_pb5done:
	s_mov_b32 s100, 4
	s_mov_b32 s84, 0
	s_branch .Lcq_entry
.Lcq_pb6done:
	s_mov_b32 s100, 1
	s_mov_b32 s84, 0
	s_branch .Lcq_entry
.Lcq_to_rms:
	s_mov_b32 s100, 0
.Lcq_rms_fix:
	v_ashrrev_i32_e32 v35, 31, v34

; __global__ void __launch_bounds__(512) fwd(Args a_) {
;     ...
;         } else if (PHM(3) && sp == 3) { PHASE_PROLOGUE
;             const unsigned* kmx = (const unsigned*)(a.ws + WS_CTL) + 8192 + 64 * (8 + 2 * L);
;             const float kb0 = 8.f * 1.01f * __uint_as_float(kmx[0]), kb1 = 8.f * 1.01f * __uint_as_float(kmx[64]);
;             const int gwx = ((G & 7) == 0 ? (bx & 7) * (G >> 3) + (bx >> 3) : bx) * 8 + wave;
;             for (int k = gwx; k < 2048; k += NGW) { nsa_item8(c, 2047 - (k >> 1), 1 - (k & 1), lds, wave, lane, (k & 1) ? kb0 : kb1); nsa_item8(c, k >> 1, k & 1, lds, wave, lane, (k & 1) ? kb1 : kb0); }
.Lcq_call3:
	s_mov_b32 s100, 6
	s_mov_b32 s84, 1
	s_branch .Lcq_entry
